# adds: residual-GEMM epilogue keeps 15 residual-tile loads in flight (ring of registers, counted vmcnt) instead of 4 load-wait round trips
# baseline (speedup 1.0000x reference)
; #define GAS __attribute__((address_space(1)))
; #define COLS_LOOP _Pragma("unroll") for (int bj = 0; bj < 2; ++bj) _Pragma("unroll") for (int n = 0; n < 2; ++n)
;   DI void operator()(const AccT& acc, const Unit& u, int wr, int wc, int fr, int fq) const {
;     ...
;     char* hb = (char*)((u.pm < 128 ? out + (size_t)u.pm * 256 * D : hctx + (size_t)(u.pm - 128) * 256 * D) + u.pn * 256);
;     const char* hs = (const char*)((u.pm < 128 ? hsrc + (size_t)u.pm * 256 * D : hctx + (size_t)(u.pm - 128) * 256 * D) + u.pn * 256);
;     const char* gp = (const char*)(gate + (size_t)b * NMODW + u.pn * 256);
;     f32x4 gv[2][2];
;     COLS_LOOP gv[bj][n] = ld4p(gp + (bj * 128 + n * 16) * 4, c0);
;     __builtin_amdgcn_sched_barrier(0);
;     COLS_LOOP gv[bj][n] = gv[bj][n] * coef;
; #pragma unroll
;     for (int ai = 0; ai < 2; ++ai) {
;       f32x4 hv[4][2][2];
; #pragma unroll
;       for (int m = 0; m < 4; ++m) { const char* rs_ = hs + (size_t)(ai * 128 + m * 16) * D * 4;
;         COLS_LOOP hv[m][bj][n] = *(const GAS f32x4*)(rs_ + (bj * 128 + n * 16) * 4 + o0); }
; #pragma unroll
;       for (int m = 0; m < 4; ++m) { char* rb = hb + (size_t)(ai * 128 + m * 16) * D * 4;
;         COLS_LOOP *(GAS f32x4*)(rb + (bj * 128 + n * 16) * 4 + o0) = hv[m][bj][n] + gv[bj][n] * acc[ai][bj][m][n]; }
.LBB0_829:
	s_andn2_b64 vcc, exec, s[38:39]
	s_cbranch_vccnz .LBB0_816
	s_ashr_i32 s35, s86, 31
	s_and_b64 s[38:39], s[30:31], exec
	s_cselect_b32 s35, s35, 0
	s_cselect_b32 s34, s86, s34
	s_cselect_b32 s86, s27, s25
	s_cselect_b32 s88, s26, s24
	s_lshl_b64 s[38:39], s[34:35], 20
	s_add_u32 s88, s88, s38
	s_addc_u32 s89, s86, s39
	s_lshl_b32 s34, s87, 8
	s_ashr_i32 s35, s34, 31
	s_lshl_b64 s[86:87], s[34:35], 2
	s_add_u32 s34, s88, s86
	s_addc_u32 s35, s89, s87
	s_and_b64 s[30:31], s[30:31], exec
	s_cselect_b32 s31, s63, s24
	s_cselect_b32 s30, s62, s25
	s_add_u32 s31, s31, s38
	s_addc_u32 s30, s30, s39
	s_lshl_b64 s[14:15], s[14:15], 2
	s_add_u32 s14, s64, s14
	s_addc_u32 s15, s65, s15
	s_add_u32 s14, s14, s86
	s_addc_u32 s15, s15, s87
	global_load_dwordx4 v[132:135], v130, s[14:15]
	global_load_dwordx4 v[136:139], v130, s[14:15] offset:64
	global_load_dwordx4 v[140:143], v130, s[14:15] offset:512
	global_load_dwordx4 v[144:147], v130, s[14:15] offset:576
	s_add_u32 s14, s31, s86
	s_addc_u32 s15, s30, s87
	v_lshl_add_u64 v[166:167], s[34:35], 0, v[0:1]
	s_add_u32 s98, s14, 0x0
	s_addc_u32 s99, s15, 0
	global_load_dwordx4 v[204:207], v0, s[98:99]
	global_load_dwordx4 v[208:211], v0, s[98:99] offset:64
	global_load_dwordx4 v[226:229], v0, s[98:99] offset:512
	global_load_dwordx4 v[238:241], v0, s[98:99] offset:576
	s_add_u32 s98, s14, 0x10000
	s_addc_u32 s99, s15, 0
	global_load_dwordx4 v[242:245], v0, s[98:99]
	global_load_dwordx4 v[246:249], v0, s[98:99] offset:64
	global_load_dwordx4 v[216:219], v0, s[98:99] offset:512
	global_load_dwordx4 v[220:223], v0, s[98:99] offset:576
	s_add_u32 s98, s14, 0x20000
	s_addc_u32 s99, s15, 0
	global_load_dwordx4 v[148:151], v0, s[98:99]
	global_load_dwordx4 v[152:155], v0, s[98:99] offset:64
	global_load_dwordx4 v[168:171], v0, s[98:99] offset:512
	global_load_dwordx4 v[172:175], v0, s[98:99] offset:576
	s_add_u32 s98, s14, 0x30000
	s_addc_u32 s99, s15, 0
	global_load_dwordx4 v[176:179], v0, s[98:99]
	global_load_dwordx4 v[180:183], v0, s[98:99] offset:64
	global_load_dwordx4 v[198:201], v0, s[98:99] offset:512
	s_waitcnt vmcnt(14)
	v_pk_mul_f32 v[132:133], v[132:133], s[10:11]
	v_pk_mul_f32 v[134:135], v[134:135], s[12:13]
	v_pk_mul_f32 v[136:137], v[136:137], s[10:11]
	v_pk_mul_f32 v[138:139], v[138:139], s[12:13]
	v_pk_mul_f32 v[140:141], v[140:141], s[10:11]
	v_pk_mul_f32 v[142:143], v[142:143], s[12:13]
	v_pk_mul_f32 v[144:145], v[144:145], s[10:11]
	v_pk_mul_f32 v[146:147], v[146:147], s[12:13]
	v_pk_fma_f32 v[126:127], v[126:127], v[132:133], v[204:205]
	v_pk_fma_f32 v[128:129], v[128:129], v[134:135], v[206:207]
	s_add_u32 s100, s34, 0x0
	s_addc_u32 s101, s35, 0
	global_store_dwordx4 v0, v[126:129], s[100:101]
	global_load_dwordx4 v[204:207], v0, s[98:99] offset:576
	s_waitcnt vmcnt(15)
	v_pk_fma_f32 v[122:123], v[122:123], v[136:137], v[208:209]
	v_pk_fma_f32 v[124:125], v[124:125], v[138:139], v[210:211]
	global_store_dwordx4 v0, v[122:125], s[100:101] offset:64
	s_add_u32 s98, s14, 0x80000
	s_addc_u32 s99, s15, 0
	global_load_dwordx4 v[208:211], v0, s[98:99]
	s_waitcnt vmcnt(16)
	v_pk_fma_f32 v[114:115], v[114:115], v[140:141], v[226:227]
	v_pk_fma_f32 v[116:117], v[116:117], v[142:143], v[228:229]
	global_store_dwordx4 v0, v[114:117], s[100:101] offset:512
	global_load_dwordx4 v[226:229], v0, s[98:99] offset:64
	s_waitcnt vmcnt(17)
	v_pk_fma_f32 v[110:111], v[110:111], v[144:145], v[238:239]
	v_pk_fma_f32 v[112:113], v[112:113], v[146:147], v[240:241]
	global_store_dwordx4 v0, v[110:113], s[100:101] offset:576
	global_load_dwordx4 v[238:241], v0, s[98:99] offset:512
	s_waitcnt vmcnt(18)
	v_pk_fma_f32 v[118:119], v[118:119], v[132:133], v[242:243]
	v_pk_fma_f32 v[120:121], v[120:121], v[134:135], v[244:245]
	s_add_u32 s100, s34, 0x10000
	s_addc_u32 s101, s35, 0
	global_store_dwordx4 v0, v[118:121], s[100:101]
	global_load_dwordx4 v[242:245], v0, s[98:99] offset:576
	s_waitcnt vmcnt(19)
	v_pk_fma_f32 v[106:107], v[106:107], v[136:137], v[246:247]
	v_pk_fma_f32 v[108:109], v[108:109], v[138:139], v[248:249]
	global_store_dwordx4 v0, v[106:109], s[100:101] offset:64
	s_add_u32 s98, s14, 0x90000
	s_addc_u32 s99, s15, 0
	global_load_dwordx4 v[246:249], v0, s[98:99]
	s_waitcnt vmcnt(20)
	v_pk_fma_f32 v[98:99], v[98:99], v[140:141], v[216:217]
	v_pk_fma_f32 v[100:101], v[100:101], v[142:143], v[218:219]
	global_store_dwordx4 v0, v[98:101], s[100:101] offset:512
	global_load_dwordx4 v[216:219], v0, s[98:99] offset:64
	s_waitcnt vmcnt(21)
	v_pk_fma_f32 v[94:95], v[94:95], v[144:145], v[220:221]
	v_pk_fma_f32 v[96:97], v[96:97], v[146:147], v[222:223]
	global_store_dwordx4 v0, v[94:97], s[100:101] offset:576
	global_load_dwordx4 v[220:223], v0, s[98:99] offset:512
	s_waitcnt vmcnt(22)
	v_pk_fma_f32 v[102:103], v[102:103], v[132:133], v[148:149]
	v_pk_fma_f32 v[104:105], v[104:105], v[134:135], v[150:151]
	s_add_u32 s100, s34, 0x20000
	s_addc_u32 s101, s35, 0
	global_store_dwordx4 v0, v[102:105], s[100:101]
	global_load_dwordx4 v[148:151], v0, s[98:99] offset:576
	s_waitcnt vmcnt(23)
; #define GAS __attribute__((address_space(1)))
; #define COLS_LOOP _Pragma("unroll") for (int bj = 0; bj < 2; ++bj) _Pragma("unroll") for (int n = 0; n < 2; ++n)
;   DI void operator()(const AccT& acc, const Unit& u, int wr, int wc, int fr, int fq) const {
;     ...
;     for (int ai = 0; ai < 2; ++ai) {
;       f32x4 hv[4][2][2];
; #pragma unroll
;       for (int m = 0; m < 4; ++m) { const char* rs_ = hs + (size_t)(ai * 128 + m * 16) * D * 4;
;         COLS_LOOP hv[m][bj][n] = *(const GAS f32x4*)(rs_ + (bj * 128 + n * 16) * 4 + o0); }
; #pragma unroll
;       for (int m = 0; m < 4; ++m) { char* rb = hb + (size_t)(ai * 128 + m * 16) * D * 4;
;         COLS_LOOP *(GAS f32x4*)(rb + (bj * 128 + n * 16) * 4 + o0) = hv[m][bj][n] + gv[bj][n] * acc[ai][bj][m][n]; }
	v_pk_fma_f32 v[90:91], v[90:91], v[136:137], v[152:153]
	v_pk_fma_f32 v[92:93], v[92:93], v[138:139], v[154:155]
	global_store_dwordx4 v0, v[90:93], s[100:101] offset:64
	s_add_u32 s98, s14, 0xa0000
	s_addc_u32 s99, s15, 0
	global_load_dwordx4 v[152:155], v0, s[98:99]
	s_waitcnt vmcnt(24)
	v_pk_fma_f32 v[86:87], v[86:87], v[140:141], v[168:169]
	v_pk_fma_f32 v[88:89], v[88:89], v[142:143], v[170:171]
	global_store_dwordx4 v0, v[86:89], s[100:101] offset:512
	global_load_dwordx4 v[168:171], v0, s[98:99] offset:64
	s_waitcnt vmcnt(25)
	v_pk_fma_f32 v[78:79], v[78:79], v[144:145], v[172:173]
	v_pk_fma_f32 v[80:81], v[80:81], v[146:147], v[174:175]
	global_store_dwordx4 v0, v[78:81], s[100:101] offset:576
	global_load_dwordx4 v[172:175], v0, s[98:99] offset:512
	s_waitcnt vmcnt(26)
	v_pk_fma_f32 v[82:83], v[82:83], v[132:133], v[176:177]
	v_pk_fma_f32 v[84:85], v[84:85], v[134:135], v[178:179]
	s_add_u32 s100, s34, 0x30000
	s_addc_u32 s101, s35, 0
	global_store_dwordx4 v0, v[82:85], s[100:101]
	global_load_dwordx4 v[176:179], v0, s[98:99] offset:576
	s_waitcnt vmcnt(27)
	v_pk_fma_f32 v[74:75], v[74:75], v[136:137], v[180:181]
	v_pk_fma_f32 v[76:77], v[76:77], v[138:139], v[182:183]
	global_store_dwordx4 v0, v[74:77], s[100:101] offset:64
	s_add_u32 s98, s14, 0xb0000
	s_addc_u32 s99, s15, 0
	global_load_dwordx4 v[180:183], v0, s[98:99]
	s_waitcnt vmcnt(28)
	v_pk_fma_f32 v[70:71], v[70:71], v[140:141], v[198:199]
	v_pk_fma_f32 v[72:73], v[72:73], v[142:143], v[200:201]
	global_store_dwordx4 v0, v[70:73], s[100:101] offset:512
	global_load_dwordx4 v[198:201], v0, s[98:99] offset:64
	s_waitcnt vmcnt(28)
	v_pk_fma_f32 v[66:67], v[66:67], v[144:145], v[204:205]
	v_pk_fma_f32 v[68:69], v[68:69], v[146:147], v[206:207]
	global_store_dwordx4 v0, v[66:69], s[100:101] offset:576
	global_load_dwordx4 v[204:207], v0, s[98:99] offset:512
	s_waitcnt vmcnt(28)
	v_pk_fma_f32 v[62:63], v[62:63], v[132:133], v[208:209]
	v_pk_fma_f32 v[64:65], v[64:65], v[134:135], v[210:211]
	s_add_u32 s100, s34, 0x80000
	s_addc_u32 s101, s35, 0
	global_store_dwordx4 v0, v[62:65], s[100:101]
	global_load_dwordx4 v[208:211], v0, s[98:99] offset:576
	s_waitcnt vmcnt(28)
	v_pk_fma_f32 v[58:59], v[58:59], v[136:137], v[226:227]
	v_pk_fma_f32 v[60:61], v[60:61], v[138:139], v[228:229]
	global_store_dwordx4 v0, v[58:61], s[100:101] offset:64
	s_waitcnt vmcnt(27)
	v_pk_fma_f32 v[50:51], v[50:51], v[140:141], v[238:239]
	v_pk_fma_f32 v[52:53], v[52:53], v[142:143], v[240:241]
	global_store_dwordx4 v0, v[50:53], s[100:101] offset:512
	s_waitcnt vmcnt(26)
	v_pk_fma_f32 v[46:47], v[46:47], v[144:145], v[242:243]
	v_pk_fma_f32 v[48:49], v[48:49], v[146:147], v[244:245]
	global_store_dwordx4 v0, v[46:49], s[100:101] offset:576
	s_waitcnt vmcnt(25)
	v_pk_fma_f32 v[54:55], v[54:55], v[132:133], v[246:247]
	v_pk_fma_f32 v[56:57], v[56:57], v[134:135], v[248:249]
	s_add_u32 s100, s34, 0x90000
	s_addc_u32 s101, s35, 0
	global_store_dwordx4 v0, v[54:57], s[100:101]
	s_waitcnt vmcnt(24)
	v_pk_fma_f32 v[42:43], v[42:43], v[136:137], v[216:217]
	v_pk_fma_f32 v[44:45], v[44:45], v[138:139], v[218:219]
	global_store_dwordx4 v0, v[42:45], s[100:101] offset:64
	s_waitcnt vmcnt(23)
	v_pk_fma_f32 v[34:35], v[34:35], v[140:141], v[220:221]
	v_pk_fma_f32 v[36:37], v[36:37], v[142:143], v[222:223]
	global_store_dwordx4 v0, v[34:37], s[100:101] offset:512
	s_waitcnt vmcnt(22)
	v_pk_fma_f32 v[30:31], v[30:31], v[144:145], v[148:149]
	v_pk_fma_f32 v[32:33], v[32:33], v[146:147], v[150:151]
	global_store_dwordx4 v0, v[30:33], s[100:101] offset:576
	s_waitcnt vmcnt(21)
	v_pk_fma_f32 v[38:39], v[38:39], v[132:133], v[152:153]
	v_pk_fma_f32 v[40:41], v[40:41], v[134:135], v[154:155]
	s_add_u32 s100, s34, 0xa0000
	s_addc_u32 s101, s35, 0
	global_store_dwordx4 v0, v[38:41], s[100:101]
	s_waitcnt vmcnt(20)
	v_pk_fma_f32 v[26:27], v[26:27], v[136:137], v[168:169]
	v_pk_fma_f32 v[28:29], v[28:29], v[138:139], v[170:171]
	global_store_dwordx4 v0, v[26:29], s[100:101] offset:64
	s_waitcnt vmcnt(19)
	v_pk_fma_f32 v[18:19], v[18:19], v[140:141], v[172:173]
	v_pk_fma_f32 v[20:21], v[20:21], v[142:143], v[174:175]
	global_store_dwordx4 v0, v[18:21], s[100:101] offset:512
	s_waitcnt vmcnt(18)
	v_pk_fma_f32 v[10:11], v[10:11], v[144:145], v[176:177]
	v_pk_fma_f32 v[12:13], v[12:13], v[146:147], v[178:179]
	global_store_dwordx4 v0, v[10:13], s[100:101] offset:576
	s_waitcnt vmcnt(17)
	v_pk_fma_f32 v[22:23], v[22:23], v[132:133], v[180:181]
	v_pk_fma_f32 v[24:25], v[24:25], v[134:135], v[182:183]
	s_add_u32 s100, s34, 0xb0000
	s_addc_u32 s101, s35, 0
	global_store_dwordx4 v0, v[22:25], s[100:101]
	s_waitcnt vmcnt(16)
	v_pk_fma_f32 v[14:15], v[14:15], v[136:137], v[198:199]
	v_pk_fma_f32 v[16:17], v[16:17], v[138:139], v[200:201]
	global_store_dwordx4 v0, v[14:17], s[100:101] offset:64
	s_waitcnt vmcnt(15)
	v_pk_fma_f32 v[6:7], v[6:7], v[140:141], v[204:205]
	v_pk_fma_f32 v[8:9], v[8:9], v[142:143], v[206:207]
	global_store_dwordx4 v0, v[6:9], s[100:101] offset:512
	s_waitcnt vmcnt(14)
	v_pk_fma_f32 v[2:3], v[2:3], v[144:145], v[208:209]
	v_pk_fma_f32 v[4:5], v[4:5], v[146:147], v[210:211]
	s_mov_b32 s14, 0xb0000
	s_mov_b32 s15, 0x80000
	s_mov_b32 s30, 0x90000
	s_mov_b32 s31, 0xa0000
	s_mov_b32 s68, 0x10000
	s_mov_b32 s71, 0x20000
	s_mov_b32 s69, 0x30000
	s_mov_b32 s33, 0x80000
	s_branch .LBB0_816
